# quant_dn moved into the gate/up GEMM K-loop as a side job (3 loop bodies: plain / row load / item store), P6b quant_dn loop dropped; on top of m1 micro-edits
# speedup vs baseline: 1.0141x; 1.0029x over previous
.LBB0_1202:
	s_or_b64 exec, exec, s[6:7]
	s_waitcnt lgkmcnt(0)
	v_mov_b32_e32 v0, v234
	s_barrier
	v_mbcnt_lo_u32_b32 v223, -1, 0
	v_mbcnt_hi_u32_b32 v223, -1, v223
	v_and_b32_e32 v224, 7, v223
	v_lshrrev_b32_e32 v225, 3, v223
	v_lshlrev_b32_e32 v226, 4, v224
	v_lshl_add_u32 v223, v225, 18, v226
	v_mul_u32_u24_e32 v224, 0xac00, v224
	v_lshl_add_u32 v224, v225, 4, v224
	v_add_u32_e32 v224, 0x12f00000, v224
	v_mov_b32_e32 v220, 0
	v_mov_b32_e32 v225, 0
	v_mov_b32_e32 v252, 0
	v_mov_b32_e32 v253, 0
	v_cvt_f32_u32_e32 v244, s94
	v_rcp_iflag_f32_e32 v244, v244
	s_nop 1
	v_mul_f32_e32 v244, 0x4f7ffffe, v244
	v_cvt_u32_f32_e32 v244, v244
	s_nop 1
	v_readfirstlane_b32 s75, v244
	s_sub_i32 s76, 0, s94
	s_mul_i32 s76, s76, s75
	s_mul_hi_u32 s76, s75, s76
	s_add_i32 s75, s75, s76
	s_mov_b32 s77, 0x2b00
	s_mul_hi_u32 s76, s77, s75
	s_mul_i32 s98, s76, s94
	s_sub_i32 s77, s77, s98
	s_add_i32 s98, s76, 1
	s_sub_i32 s99, s77, s94
	s_cmp_ge_u32 s77, s94
	s_cselect_b32 s76, s98, s76
	s_cselect_b32 s77, s99, s77
	s_add_i32 s98, s76, 1
	s_sub_i32 s99, s77, s94
	s_cmp_ge_u32 s77, s94
	s_cselect_b32 s76, s98, s76
	s_cselect_b32 s77, s99, s77
	s_mul_i32 s84, s86, s76
	s_min_u32 s98, s86, s77
	s_add_u32 s84, s84, s98
	s_cmp_lt_u32 s86, s77
	s_addc_u32 s87, s84, s76
	s_min_u32 s84, s84, 0x2b00
	s_min_u32 s87, s87, 0x2b00
	s_lshl_b32 s84, s84, 4
	s_lshl_b32 s87, s87, 4
	s_mov_b32 s89, -1
	s_mov_b32 s32, 0
	s_lshr_b32 s77, s84, 5
	s_mul_i32 s77, s77, 0x17d07
	s_lshr_b32 s77, s77, 22
	s_min_u32 s77, s77, 0x7f
	s_lshl_b32 s75, s77, 7
	s_add_u32 s75, s75, 0xc0000
	v_and_b32_e32 v240, 0x70, v223
	v_add_u32_e32 v240, s75, v240
	global_load_dwordx4 v[240:243], v240, s[96:97]
	s_abs_i32 s8, s92
	v_cvt_f32_u32_e32 v0, s8
	s_sub_i32 s9, 0, s8
	s_ashr_i32 s3, s92, 31
	s_mov_b32 s14, 0
	v_rcp_iflag_f32_e32 v0, v0
	v_mov_b32_e32 v221, v245
	v_mov_b32_e32 v222, v249
	v_mul_f32_e32 v1, 0x4f7ffffe, v0
	v_cvt_u32_f32_e32 v1, v1
	s_nop 0
	v_readfirstlane_b32 s6, v1
	s_mul_i32 s7, s9, s6
	s_mul_hi_u32 s7, s6, s7
	s_add_i32 s6, s6, s7
	s_mul_hi_u32 s6, s6, 0xac0
	s_mul_i32 s7, s6, s8
	s_sub_i32 s7, 0xac0, s7
	s_add_i32 s10, s6, 1
	s_sub_i32 s11, s7, s8
	s_cmp_ge_u32 s7, s8
	s_cselect_b32 s6, s10, s6
	s_cselect_b32 s7, s11, s7
	s_add_i32 s10, s6, 1
	s_cmp_ge_u32 s7, s8
	s_cselect_b32 s6, s10, s6
	s_xor_b32 s6, s6, s3
	s_sub_i32 s10, s6, s3
	s_mul_i32 s3, s10, s92
	s_sub_i32 s11, 0xac0, s3
	s_sub_i32 s3, s2, s11
	s_ashr_i32 s6, s3, 31
	s_and_b32 s6, s6, s92
	s_add_i32 s3, s6, s3
	s_cmpk_lg_i32 s92, 0x100
	s_cselect_b64 s[6:7], -1, 0
	s_and_b64 vcc, exec, s[6:7]
	s_cbranch_vccz .LBB0_1206
	s_cmpk_gt_i32 s3, 0x157
	s_cbranch_scc1 .LBB0_1205
	v_mul_f32_e32 v0, 0x4f7ffffe, v0
	v_cvt_u32_f32_e32 v0, v0
	s_sub_i32 s14, s92, s3
	s_add_i32 s15, s14, 0x157
	s_sub_i32 s14, 0xfffffea9, s14
	s_xor_b32 s16, s15, s92
	s_max_i32 s14, s15, s14
	v_readfirstlane_b32 s15, v0
	s_mul_i32 s9, s9, s15
	s_mul_hi_u32 s9, s15, s9
	s_add_i32 s15, s15, s9
	s_mul_hi_u32 s9, s14, s15
	s_mul_i32 s15, s9, s8
	s_sub_i32 s14, s14, s15
	s_ashr_i32 s16, s16, 31
	s_add_i32 s15, s9, 1
	s_sub_i32 s17, s14, s8
	s_cmp_ge_u32 s14, s8
	s_cselect_b32 s9, s15, s9
	s_cselect_b32 s14, s17, s14
	s_add_i32 s15, s9, 1
	s_cmp_ge_u32 s14, s8
	s_cselect_b32 s8, s15, s9
	s_xor_b32 s8, s8, s16
	s_sub_i32 s8, s8, s16
	s_max_i32 s14, s8, 0

.LBB0_1221:
	s_add_u32 s14, s96, 0xa0000
	s_addc_u32 s15, s97, 0
	s_add_u32 s16, s96, 0x80000
	s_addc_u32 s17, s97, 0
	s_lshl_b32 s20, s20, 5
	s_and_b32 s50, s20, 0x60
	s_mov_b64 s[20:21], 0x80
	s_add_i32 m0, s45, 0x18000
	v_lshl_add_u64 v[6:7], v[6:7], 0, s[20:21]
	s_lshl_b32 s49, s8, 6
	s_lshl_b32 s8, s8, 13
	s_lshl_b32 s23, s50, 7
	s_waitcnt vmcnt(2)
	s_barrier
	global_load_lds_dwordx4 v[6:7], off
	v_lshl_add_u64 v[4:5], v[4:5], 0, s[20:21]
	s_add_i32 m0, s45, 0x1a000
	s_add_i32 s51, s45, 0x8000
	s_add_i32 s52, s45, 0xa000
	global_load_lds_dwordx4 v[4:5], off
	v_lshl_add_u64 v[0:1], v[0:1], 0, s[20:21]
	s_mov_b32 m0, s51
	s_add_u32 s24, s38, 0x80080
	global_load_lds_dwordx4 v[0:1], off
	v_lshl_add_u64 v[0:1], v[2:3], 0, s[20:21]
	s_mov_b32 m0, s52
	s_addc_u32 s25, s39, 0
	global_load_lds_dwordx4 v[0:1], off
	s_add_i32 m0, s45, 0x1c000
	v_lshl_add_u64 v[0:1], s[24:25], 0, v[130:131]
	global_load_lds_dwordx4 v[0:1], off
	v_lshl_add_u64 v[0:1], s[24:25], 0, v[134:135]
	s_add_i32 m0, s45, 0x1e000
	v_bfe_u32 v176, v8, 4, 2
	global_load_lds_dwordx4 v[0:1], off
	v_and_b32_e32 v175, 15, v8
	v_lshlrev_b32_e32 v0, 4, v176
	v_lshlrev_b32_e32 v1, 2, v8
	v_lshl_or_b32 v0, v175, 6, v0
	v_and_b32_e32 v1, 32, v1
	v_bitop3_b32 v2, v0, s8, v1 bitop3:0xde
	v_bitop3_b32 v177, v0, s23, v1 bitop3:0xde
	v_lshlrev_b32_e32 v0, 15, v9
	v_and_b32_e32 v0, 0xffff0000, v0
	v_lshl_add_u32 v0, v10, 12, v0
	v_and_b32_e32 v1, 1, v9
	v_lshl_or_b32 v0, v1, 6, v0
	v_lshl_add_u32 v136, v11, 1, v0
	v_lshlrev_b32_e32 v0, 15, v12
	v_and_b32_e32 v0, 0xffff0000, v0
	s_waitcnt vmcnt(6)
	s_cmpk_lt_u32 s22, 0x100
	v_lshl_add_u32 v0, v13, 12, v0
	v_and_b32_e32 v1, 1, v12
	s_cselect_b64 s[22:23], -1, 0
	s_cmp_lt_i32 s3, 64
	v_lshl_or_b32 v0, v1, 6, v0
	s_cselect_b64 s[24:25], -1, 0
	s_lshl_b32 s53, s3, 2
	s_add_i32 s54, s3, 0xc0
	v_mov_b32_e32 v137, v131
	v_lshl_add_u32 v138, v14, 1, v0
	v_mov_b32_e32 v139, v131
	s_add_i32 s55, 0, 0x10000
	s_add_i32 s60, 0, 0x14000
	v_add_u32_e32 v178, 0, v2
	s_mov_b32 s26, 0x3c010204
	s_mov_b32 s61, 0x15800
	s_movk_i32 s62, 0x5600
	s_mov_b32 s63, 0
	s_barrier
	s_cmp_lt_u32 s84, s87
	s_cbranch_scc0 .Lq_init_done
	s_mov_b32 s75, 0x42fe0000
	v_div_scale_f32 v236, vcc, v240, v240, s75
	v_rcp_f32_e32 v237, v236
	s_nop 1
	v_fma_f32 v238, -v236, v237, 1.0
	v_fmac_f32_e32 v237, v238, v237
	v_div_scale_f32 v238, vcc, s75, v240, s75
	v_mul_f32_e32 v239, v238, v237
	v_fma_f32 v244, -v236, v239, v238
	v_fmac_f32_e32 v239, v244, v237
	v_fma_f32 v236, -v236, v239, v238
	s_nop 4
	v_div_fmas_f32 v236, v236, v237, v239
	v_div_fixup_f32 v236, v236, v240, s75
	v_cmp_lt_f32_e32 vcc, 0, v240
	s_nop 1
	v_cndmask_b32_e32 v220, 0, v236, vcc
	v_div_scale_f32 v236, vcc, v241, v241, s75
	v_rcp_f32_e32 v237, v236
	s_nop 1
	v_fma_f32 v238, -v236, v237, 1.0
	v_fmac_f32_e32 v237, v238, v237
	v_div_scale_f32 v238, vcc, s75, v241, s75
	v_mul_f32_e32 v239, v238, v237
	v_fma_f32 v244, -v236, v239, v238
	v_fmac_f32_e32 v239, v244, v237
	v_fma_f32 v236, -v236, v239, v238
	s_nop 4
	v_div_fmas_f32 v236, v236, v237, v239
	v_div_fixup_f32 v236, v236, v241, s75
	v_cmp_lt_f32_e32 vcc, 0, v241
	s_nop 1
	v_cndmask_b32_e32 v225, 0, v236, vcc
	v_div_scale_f32 v236, vcc, v242, v242, s75
	v_rcp_f32_e32 v237, v236
	s_nop 1
	v_fma_f32 v238, -v236, v237, 1.0
	v_fmac_f32_e32 v237, v238, v237
	v_div_scale_f32 v238, vcc, s75, v242, s75
	v_mul_f32_e32 v239, v238, v237
	v_fma_f32 v244, -v236, v239, v238
	v_fmac_f32_e32 v239, v244, v237
	v_fma_f32 v236, -v236, v239, v238
	s_nop 4
	v_div_fmas_f32 v236, v236, v237, v239
	v_div_fixup_f32 v236, v236, v242, s75
	v_cmp_lt_f32_e32 vcc, 0, v242
	s_nop 1
	v_cndmask_b32_e32 v252, 0, v236, vcc
	v_div_scale_f32 v236, vcc, v243, v243, s75
	v_rcp_f32_e32 v237, v236
	s_nop 1
	v_fma_f32 v238, -v236, v237, 1.0
	v_fmac_f32_e32 v237, v238, v237
	v_div_scale_f32 v238, vcc, s75, v243, s75
	v_mul_f32_e32 v239, v238, v237
	v_fma_f32 v244, -v236, v239, v238
	v_fmac_f32_e32 v239, v244, v237
	v_fma_f32 v236, -v236, v239, v238
	s_nop 4
	v_div_fmas_f32 v236, v236, v237, v239
	v_div_fixup_f32 v236, v236, v243, s75
	v_cmp_lt_f32_e32 vcc, 0, v243
	s_nop 1
	v_cndmask_b32_e32 v253, 0, v236, vcc
	s_lshr_b32 s76, s84, 4
	s_lshr_b32 s77, s76, 1
	s_mul_i32 s77, s77, 0x17d07
	s_lshr_b32 s77, s77, 22
	s_mov_b32 s89, s77
	s_mul_i32 s75, s77, 86
	s_sub_u32 s76, s76, s75
	s_lshl_b32 s76, s76, 7
	s_mul_i32 s98, s77, 0x56000
	s_add_u32 s98, s98, s76
	s_add_u32 s98, s96, s98
	s_addc_u32 s99, s97, 0
	s_and_b32 s75, s84, 15
	s_add_u32 s76, s76, s75
	s_lshl_b32 s76, s76, 14
	s_lshl_b32 s77, s77, 7
	s_add_u32 s76, s76, s77
	s_load_dwordx2 s[100:101], s[0:1], 0x88
	s_waitcnt lgkmcnt(0)
	s_add_u32 s100, s100, s76
	s_addc_u32 s101, s101, 0
	s_mov_b32 s32, 1
.Lq_init_done:
	s_branch .LBB0_1224
.LBB0_1222:
	s_mov_b64 s[30:31], 0

.LBB0_1236:
	s_lshl_b32 s8, s64, 20
	s_and_b32 s8, s8, 0xff00000
	s_add_u32 s8, s43, s8
	s_addc_u32 s29, s44, 0
	s_lshl_b32 s28, s65, 7
	s_and_b32 s34, s28, 0x7fff80
	s_add_u32 s28, s8, s34
	s_addc_u32 s29, s29, 0
	s_lshl_b32 s8, s64, 12
	s_and_b32 s8, s8, 0xff00000
	v_readlane_b32 s68, v254, 26
	v_readlane_b32 s69, v254, 27
	s_add_u32 s8, s68, s8
	s_addc_u32 s35, s69, 0
	s_add_u32 s34, s8, s34
	s_addc_u32 s35, s35, 0
	s_ashr_i32 s8, s40, 16
	s_cmp_lt_i32 s8, 1
	s_cbranch_scc1 .LBB0_1247
	s_and_b64 s[40:41], s[30:31], exec
	s_cselect_b32 s67, s29, s37
	s_cselect_b32 s68, s28, s36
	s_cselect_b32 s69, s35, s39
	s_cselect_b32 s70, s34, s38
	s_add_i32 s71, s8, -2
	s_add_u32 s36, s36, 0x80080
	s_addc_u32 s37, s37, 0
	s_add_u32 s72, s38, 0x100
	s_addc_u32 s73, s39, 0
	s_mov_b32 s38, 0
	v_mov_b64_e32 v[0:1], 0
	v_mov_b64_e32 v[2:3], 0
	v_mov_b64_e32 v[4:5], 0
	v_mov_b64_e32 v[6:7], 0
	v_mov_b64_e32 v[8:9], 0
	v_mov_b64_e32 v[10:11], 0
	v_mov_b64_e32 v[12:13], 0
	v_mov_b64_e32 v[14:15], 0
	v_mov_b64_e32 v[20:21], 0
	v_mov_b64_e32 v[22:23], 0
	v_mov_b64_e32 v[28:29], 0
	v_mov_b64_e32 v[30:31], 0
	v_mov_b64_e32 v[36:37], 0
	v_mov_b64_e32 v[38:39], 0
	v_mov_b64_e32 v[44:45], 0
	v_mov_b64_e32 v[46:47], 0
	v_mov_b64_e32 v[16:17], 0
	v_mov_b64_e32 v[18:19], 0
	v_mov_b64_e32 v[24:25], 0
	v_mov_b64_e32 v[26:27], 0
	v_mov_b64_e32 v[32:33], 0
	v_mov_b64_e32 v[34:35], 0
	v_mov_b64_e32 v[40:41], 0
	v_mov_b64_e32 v[42:43], 0
	v_mov_b64_e32 v[48:49], 0
	v_mov_b64_e32 v[50:51], 0
	v_mov_b64_e32 v[52:53], 0
	v_mov_b64_e32 v[54:55], 0
	v_mov_b64_e32 v[56:57], 0
	v_mov_b64_e32 v[58:59], 0
	v_mov_b64_e32 v[60:61], 0
	v_mov_b64_e32 v[62:63], 0
	v_mov_b64_e32 v[64:65], 0
	v_mov_b64_e32 v[66:67], 0
	v_mov_b64_e32 v[68:69], 0
	v_mov_b64_e32 v[70:71], 0
	v_mov_b64_e32 v[72:73], 0
	v_mov_b64_e32 v[74:75], 0
	v_mov_b64_e32 v[76:77], 0
	v_mov_b64_e32 v[78:79], 0
	v_mov_b64_e32 v[84:85], 0
	v_mov_b64_e32 v[86:87], 0
	v_mov_b64_e32 v[92:93], 0
	v_mov_b64_e32 v[94:95], 0
	v_mov_b64_e32 v[100:101], 0
	v_mov_b64_e32 v[102:103], 0
	v_mov_b64_e32 v[108:109], 0
	v_mov_b64_e32 v[110:111], 0
	v_mov_b64_e32 v[80:81], 0
	v_mov_b64_e32 v[82:83], 0
	v_mov_b64_e32 v[88:89], 0
	v_mov_b64_e32 v[90:91], 0
	v_mov_b64_e32 v[96:97], 0
	v_mov_b64_e32 v[98:99], 0
	v_mov_b64_e32 v[104:105], 0
	v_mov_b64_e32 v[106:107], 0
	v_mov_b64_e32 v[112:113], 0
	v_mov_b64_e32 v[114:115], 0
	v_mov_b64_e32 v[116:117], 0
	v_mov_b64_e32 v[118:119], 0
	v_mov_b64_e32 v[120:121], 0
	v_mov_b64_e32 v[122:123], 0
	v_mov_b64_e32 v[124:125], 0
	v_mov_b64_e32 v[126:127], 0
	s_cmp_eq_u32 s32, 0
	s_cbranch_scc0 .Lq_disp

.Lq_epi:
	v_cvt_f32_i32_e32 v140, v124
	v_cvt_f32_i32_e32 v141, v125
	v_cvt_f32_i32_e32 v124, v126
	v_cvt_f32_i32_e32 v125, v127
	v_cvt_f32_i32_e32 v142, v120
	v_cvt_f32_i32_e32 v143, v121
	v_cvt_f32_i32_e32 v120, v122
	v_cvt_f32_i32_e32 v121, v123
	v_cvt_f32_i32_e32 v144, v108
	v_cvt_f32_i32_e32 v145, v109
	v_cvt_f32_i32_e32 v122, v110
	v_cvt_f32_i32_e32 v123, v111
	v_cvt_f32_i32_e32 v146, v100
	v_cvt_f32_i32_e32 v147, v101
	v_cvt_f32_i32_e32 v126, v102
	v_cvt_f32_i32_e32 v127, v103
	v_cvt_f32_i32_e32 v116, v116
	v_cvt_f32_i32_e32 v117, v117
	v_cvt_f32_i32_e32 v108, v118
	v_cvt_f32_i32_e32 v109, v119
	v_cvt_f32_i32_e32 v112, v112
	v_cvt_f32_i32_e32 v113, v113
	v_cvt_f32_i32_e32 v110, v114
	v_cvt_f32_i32_e32 v111, v115
	v_cvt_f32_i32_e32 v114, v92
	v_cvt_f32_i32_e32 v115, v93
	v_cvt_f32_i32_e32 v100, v94
	v_cvt_f32_i32_e32 v101, v95
	v_cvt_f32_i32_e32 v118, v84
	v_cvt_f32_i32_e32 v119, v85
	v_cvt_f32_i32_e32 v102, v86
	v_cvt_f32_i32_e32 v103, v87
	v_cvt_f32_i32_e32 v104, v104
	v_cvt_f32_i32_e32 v105, v105
	v_cvt_f32_i32_e32 v84, v106
	v_cvt_f32_i32_e32 v85, v107
	v_cvt_f32_i32_e32 v96, v96
	v_cvt_f32_i32_e32 v97, v97
	v_cvt_f32_i32_e32 v86, v98
	v_cvt_f32_i32_e32 v87, v99
	v_cvt_f32_i32_e32 v148, v76
	v_cvt_f32_i32_e32 v149, v77
	v_cvt_f32_i32_e32 v92, v78
	v_cvt_f32_i32_e32 v93, v79
	v_cvt_f32_i32_e32 v152, v72
	v_cvt_f32_i32_e32 v153, v73
	v_cvt_f32_i32_e32 v94, v74
	v_cvt_f32_i32_e32 v95, v75
	v_cvt_f32_i32_e32 v98, v88
	v_cvt_f32_i32_e32 v99, v89
	v_cvt_f32_i32_e32 v76, v90
	v_cvt_f32_i32_e32 v77, v91
	v_cvt_f32_i32_e32 v106, v80
	v_cvt_f32_i32_e32 v107, v81
	v_cvt_f32_i32_e32 v78, v82
	v_cvt_f32_i32_e32 v79, v83
	v_cvt_f32_i32_e32 v154, v68
	v_cvt_f32_i32_e32 v155, v69
	v_cvt_f32_i32_e32 v80, v70
	v_cvt_f32_i32_e32 v81, v71
	v_cvt_f32_i32_e32 v158, v64
	v_cvt_f32_i32_e32 v159, v65
	v_cvt_f32_i32_e32 v82, v66
	v_cvt_f32_i32_e32 v83, v67
	v_cvt_f32_i32_e32 v64, v60
	v_cvt_f32_i32_e32 v65, v61
	v_cvt_f32_i32_e32 v66, v62
	v_cvt_f32_i32_e32 v67, v63
	v_cvt_f32_i32_e32 v60, v56
	v_cvt_f32_i32_e32 v61, v57
	v_cvt_f32_i32_e32 v62, v58
	v_cvt_f32_i32_e32 v63, v59
	v_cvt_f32_i32_e32 v70, v44
	v_cvt_f32_i32_e32 v71, v45
	v_cvt_f32_i32_e32 v74, v46
	v_cvt_f32_i32_e32 v75, v47
	v_cvt_f32_i32_e32 v68, v36
	v_cvt_f32_i32_e32 v69, v37
	v_cvt_f32_i32_e32 v72, v38
	v_cvt_f32_i32_e32 v73, v39
	v_cvt_f32_i32_e32 v46, v52
	v_cvt_f32_i32_e32 v47, v53
	v_cvt_f32_i32_e32 v52, v54
	v_cvt_f32_i32_e32 v53, v55
	v_cvt_f32_i32_e32 v44, v48
	v_cvt_f32_i32_e32 v45, v49
	v_cvt_f32_i32_e32 v48, v50
	v_cvt_f32_i32_e32 v49, v51
	v_cvt_f32_i32_e32 v54, v28
	v_cvt_f32_i32_e32 v55, v29
	v_cvt_f32_i32_e32 v58, v30
	v_cvt_f32_i32_e32 v59, v31
	v_cvt_f32_i32_e32 v50, v20
	v_cvt_f32_i32_e32 v51, v21
	v_cvt_f32_i32_e32 v56, v22
	v_cvt_f32_i32_e32 v57, v23
	v_cvt_f32_i32_e32 v22, v40
	v_cvt_f32_i32_e32 v23, v41
	v_cvt_f32_i32_e32 v30, v42
	v_cvt_f32_i32_e32 v31, v43
	v_cvt_f32_i32_e32 v20, v32
	v_cvt_f32_i32_e32 v21, v33
	v_cvt_f32_i32_e32 v28, v34
	v_cvt_f32_i32_e32 v29, v35
	v_cvt_f32_i32_e32 v34, v12
	v_cvt_f32_i32_e32 v35, v13
	v_cvt_f32_i32_e32 v38, v14
	v_cvt_f32_i32_e32 v39, v15
	v_cvt_f32_i32_e32 v32, v8
	v_cvt_f32_i32_e32 v33, v9
	v_cvt_f32_i32_e32 v36, v10
	v_cvt_f32_i32_e32 v37, v11
	v_cvt_f32_i32_e32 v10, v24
	v_cvt_f32_i32_e32 v11, v25
	v_cvt_f32_i32_e32 v14, v26
	v_cvt_f32_i32_e32 v15, v27
	v_cvt_f32_i32_e32 v8, v16
	v_cvt_f32_i32_e32 v9, v17
	v_cvt_f32_i32_e32 v12, v18
	v_cvt_f32_i32_e32 v13, v19
	v_cvt_f32_i32_e32 v4, v4
	v_cvt_f32_i32_e32 v5, v5
	v_cvt_f32_i32_e32 v6, v6
	v_cvt_f32_i32_e32 v7, v7
	v_cvt_f32_i32_e32 v0, v0
	v_cvt_f32_i32_e32 v1, v1
	v_cvt_f32_i32_e32 v2, v2
	v_cvt_f32_i32_e32 v3, v3
	s_and_b64 vcc, exec, s[22:23]
	s_cbranch_vccz .LBB0_1241

.Lq_disp:
	s_cmp_eq_u32 s32, 1
	s_cbranch_scc1 .Lq_body_L
	s_branch .Lq_body_ST
.Lq_body_L:
	s_add_i32 s74, s38, 2
	s_add_u32 s39, s36, 0xfff80080
	s_addc_u32 s40, s37, -1
	s_cmp_eq_u32 s71, s38
	s_cselect_b32 s41, s67, s40
	s_cselect_b32 s40, s68, s39
	v_add_u32_e32 v152, s55, v177
	v_add_u32_e32 v168, s60, v177
	ds_read_b128 v[140:143], v152
	ds_read_b128 v[144:147], v152 offset:1024
	ds_read_b128 v[148:151], v152 offset:2048
	ds_read_b128 v[152:155], v152 offset:3072
	ds_read_b128 v[156:159], v168
	ds_read_b128 v[160:163], v168 offset:1024
	ds_read_b128 v[164:167], v168 offset:2048
	ds_read_b128 v[168:171], v168 offset:3072
	s_cselect_b32 s38, s70, s72
	s_cselect_b32 s39, s69, s73
	v_lshl_add_u64 v[172:173], s[36:37], 0, v[136:137]
	s_add_i32 m0, s45, 0xc000
	ds_read_b128 v[180:183], v178
	ds_read_b128 v[184:187], v178 offset:1024
	ds_read_b128 v[188:191], v178 offset:2048
	ds_read_b128 v[192:195], v178 offset:3072
	ds_read_b128 v[196:199], v178 offset:4096
	ds_read_b128 v[200:203], v178 offset:5120
	ds_read_b128 v[204:207], v178 offset:6144
	ds_read_b128 v[208:211], v178 offset:7168
	global_load_lds_dwordx4 v[172:173], off
	v_lshl_add_u64 v[172:173], s[36:37], 0, v[138:139]
	s_add_i32 m0, s45, 0xe000
	s_nop 0
	global_load_lds_dwordx4 v[172:173], off
	global_load_dwordx4 v[226:229], v223, s[100:101] nt
	s_add_u32 s100, s100, 0x4000
	s_addc_u32 s101, s101, 0
	s_add_u32 s84, s84, 1
	s_waitcnt vmcnt(9)
	s_waitcnt lgkmcnt(0)
	s_barrier
	s_setprio 1
	s_waitcnt lgkmcnt(0)
	v_mfma_i32_16x16x64_i8 v[124:127], v[140:143], v[180:183], v[124:127]
	v_mfma_i32_16x16x64_i8 v[120:123], v[148:151], v[180:183], v[120:123]
	v_mfma_i32_16x16x64_i8 v[116:119], v[140:143], v[188:191], v[116:119]
	v_mfma_i32_16x16x64_i8 v[112:115], v[148:151], v[188:191], v[112:115]
	v_mfma_i32_16x16x64_i8 v[104:107], v[140:143], v[196:199], v[104:107]
	v_mfma_i32_16x16x64_i8 v[96:99], v[148:151], v[196:199], v[96:99]
	v_mfma_i32_16x16x64_i8 v[88:91], v[140:143], v[204:207], v[88:91]
	v_mfma_i32_16x16x64_i8 v[80:83], v[148:151], v[204:207], v[80:83]
	v_mfma_i32_16x16x64_i8 v[124:127], v[144:147], v[184:187], v[124:127]
	v_mfma_i32_16x16x64_i8 v[120:123], v[152:155], v[184:187], v[120:123]
	v_mfma_i32_16x16x64_i8 v[116:119], v[144:147], v[192:195], v[116:119]
	v_mfma_i32_16x16x64_i8 v[112:115], v[152:155], v[192:195], v[112:115]
	v_mfma_i32_16x16x64_i8 v[104:107], v[144:147], v[200:203], v[104:107]
	v_mfma_i32_16x16x64_i8 v[96:99], v[152:155], v[200:203], v[96:99]
	v_mfma_i32_16x16x64_i8 v[88:91], v[144:147], v[208:211], v[88:91]
	v_mfma_i32_16x16x64_i8 v[80:83], v[152:155], v[208:211], v[80:83]
	s_setprio 0
	s_setprio 1
	v_mfma_i32_16x16x64_i8 v[108:111], v[156:159], v[180:183], v[108:111]
	v_mfma_i32_16x16x64_i8 v[100:103], v[164:167], v[180:183], v[100:103]
	v_mfma_i32_16x16x64_i8 v[92:95], v[156:159], v[188:191], v[92:95]
	v_mfma_i32_16x16x64_i8 v[84:87], v[164:167], v[188:191], v[84:87]
	v_mfma_i32_16x16x64_i8 v[76:79], v[156:159], v[196:199], v[76:79]
	v_mfma_i32_16x16x64_i8 v[72:75], v[164:167], v[196:199], v[72:75]
	v_mfma_i32_16x16x64_i8 v[68:71], v[156:159], v[204:207], v[68:71]
	v_mfma_i32_16x16x64_i8 v[64:67], v[164:167], v[204:207], v[64:67]
	v_mfma_i32_16x16x64_i8 v[108:111], v[160:163], v[184:187], v[108:111]
	v_mfma_i32_16x16x64_i8 v[100:103], v[168:171], v[184:187], v[100:103]
	v_mfma_i32_16x16x64_i8 v[92:95], v[160:163], v[192:195], v[92:95]
	v_mfma_i32_16x16x64_i8 v[84:87], v[168:171], v[192:195], v[84:87]
	v_mfma_i32_16x16x64_i8 v[76:79], v[160:163], v[200:203], v[76:79]
	v_mfma_i32_16x16x64_i8 v[72:75], v[168:171], v[200:203], v[72:75]
	v_mfma_i32_16x16x64_i8 v[68:71], v[160:163], v[208:211], v[68:71]
	v_mfma_i32_16x16x64_i8 v[64:67], v[168:171], v[208:211], v[64:67]
	s_setprio 0
	s_barrier
	s_add_i32 s75, s55, s42
	v_lshl_add_u64 v[172:173], s[38:39], 0, v[130:131]
	s_mov_b32 m0, s75
	ds_read_b128 v[180:183], v178 offset:16384
	ds_read_b128 v[184:187], v178 offset:17408
	ds_read_b128 v[188:191], v178 offset:18432
	ds_read_b128 v[192:195], v178 offset:19456
	ds_read_b128 v[196:199], v178 offset:20480
	ds_read_b128 v[200:203], v178 offset:21504
	ds_read_b128 v[204:207], v178 offset:22528
	ds_read_b128 v[208:211], v178 offset:23552
	global_load_lds_dwordx4 v[172:173], off
	s_add_i32 m0, s75, 0x2000
	s_add_u32 s76, s38, 0x80000
	v_lshl_add_u64 v[212:213], s[38:39], 0, v[134:135]
	s_addc_u32 s77, s39, 0
	s_add_i32 s75, s60, s42
	global_load_lds_dwordx4 v[212:213], off
	v_lshl_add_u64 v[214:215], s[76:77], 0, v[130:131]
	s_mov_b32 m0, s75
	v_lshl_add_u64 v[216:217], s[40:41], 0, v[132:133]
	global_load_lds_dwordx4 v[214:215], off
	v_lshl_add_u64 v[214:215], s[76:77], 0, v[134:135]
	s_add_i32 m0, s75, 0x2000
	s_nop 0
	global_load_lds_dwordx4 v[214:215], off
	v_lshl_add_u64 v[214:215], s[40:41], 0, v[128:129]
	s_mov_b32 m0, s45
	s_nop 0
	global_load_lds_dwordx4 v[214:215], off
	s_mov_b32 m0, s46
	s_nop 0
	global_load_lds_dwordx4 v[216:217], off
	s_waitcnt vmcnt(9)
	s_waitcnt lgkmcnt(0)
	s_barrier
	s_setprio 1
	s_waitcnt lgkmcnt(0)
	v_mfma_i32_16x16x64_i8 v[60:63], v[140:143], v[180:183], v[60:63]
	v_mfma_i32_16x16x64_i8 v[56:59], v[148:151], v[180:183], v[56:59]
	v_mfma_i32_16x16x64_i8 v[52:55], v[140:143], v[188:191], v[52:55]
	v_mfma_i32_16x16x64_i8 v[48:51], v[148:151], v[188:191], v[48:51]
	v_mfma_i32_16x16x64_i8 v[40:43], v[140:143], v[196:199], v[40:43]
	v_mfma_i32_16x16x64_i8 v[32:35], v[148:151], v[196:199], v[32:35]
	v_mfma_i32_16x16x64_i8 v[24:27], v[140:143], v[204:207], v[24:27]
	v_mfma_i32_16x16x64_i8 v[16:19], v[148:151], v[204:207], v[16:19]
	v_mfma_i32_16x16x64_i8 v[60:63], v[144:147], v[184:187], v[60:63]
	v_mfma_i32_16x16x64_i8 v[56:59], v[152:155], v[184:187], v[56:59]
	v_mfma_i32_16x16x64_i8 v[52:55], v[144:147], v[192:195], v[52:55]
	v_mfma_i32_16x16x64_i8 v[48:51], v[152:155], v[192:195], v[48:51]
	v_mfma_i32_16x16x64_i8 v[40:43], v[144:147], v[200:203], v[40:43]
	v_mfma_i32_16x16x64_i8 v[32:35], v[152:155], v[200:203], v[32:35]
	v_mfma_i32_16x16x64_i8 v[24:27], v[144:147], v[208:211], v[24:27]
	v_mfma_i32_16x16x64_i8 v[16:19], v[152:155], v[208:211], v[16:19]
	s_setprio 0
	s_setprio 1
	v_mfma_i32_16x16x64_i8 v[44:47], v[156:159], v[180:183], v[44:47]
	v_mfma_i32_16x16x64_i8 v[36:39], v[164:167], v[180:183], v[36:39]
	v_mfma_i32_16x16x64_i8 v[28:31], v[156:159], v[188:191], v[28:31]
	v_mfma_i32_16x16x64_i8 v[20:23], v[164:167], v[188:191], v[20:23]
	v_mfma_i32_16x16x64_i8 v[12:15], v[156:159], v[196:199], v[12:15]
	v_mfma_i32_16x16x64_i8 v[8:11], v[164:167], v[196:199], v[8:11]
	v_mfma_i32_16x16x64_i8 v[4:7], v[156:159], v[204:207], v[4:7]
	v_mfma_i32_16x16x64_i8 v[0:3], v[164:167], v[204:207], v[0:3]
	v_mfma_i32_16x16x64_i8 v[44:47], v[160:163], v[184:187], v[44:47]
	v_mfma_i32_16x16x64_i8 v[36:39], v[168:171], v[184:187], v[36:39]
	v_mfma_i32_16x16x64_i8 v[28:31], v[160:163], v[192:195], v[28:31]
	v_mfma_i32_16x16x64_i8 v[20:23], v[168:171], v[192:195], v[20:23]
	v_mfma_i32_16x16x64_i8 v[12:15], v[160:163], v[200:203], v[12:15]
	v_mfma_i32_16x16x64_i8 v[8:11], v[168:171], v[200:203], v[8:11]
	v_mfma_i32_16x16x64_i8 v[4:7], v[160:163], v[208:211], v[4:7]
	v_mfma_i32_16x16x64_i8 v[0:3], v[168:171], v[208:211], v[0:3]
	s_setprio 0
	s_barrier
	s_add_i32 s75, 0, 0x18000
	s_add_i32 s76, 0, 0x1c000
	v_add_u32_e32 v152, s75, v177
	v_add_u32_e32 v168, s76, v177
	ds_read_b128 v[140:143], v152
	ds_read_b128 v[144:147], v152 offset:1024
	ds_read_b128 v[148:151], v152 offset:2048
	ds_read_b128 v[152:155], v152 offset:3072
	ds_read_b128 v[156:159], v168
	ds_read_b128 v[160:163], v168 offset:1024
	ds_read_b128 v[164:167], v168 offset:2048
	ds_read_b128 v[168:171], v168 offset:3072
	s_add_u32 s40, s40, 0x80000
	s_addc_u32 s41, s41, 0
	s_mov_b32 m0, s47
	v_lshl_add_u64 v[218:219], s[40:41], 0, v[128:129]
	ds_read_b128 v[180:183], v178 offset:32768
	ds_read_b128 v[184:187], v178 offset:33792
	ds_read_b128 v[188:191], v178 offset:34816
	ds_read_b128 v[192:195], v178 offset:35840
	ds_read_b128 v[196:199], v178 offset:36864
	ds_read_b128 v[200:203], v178 offset:37888
	ds_read_b128 v[204:207], v178 offset:38912
	ds_read_b128 v[208:211], v178 offset:39936
	global_load_lds_dwordx4 v[218:219], off
	v_lshl_add_u64 v[218:219], s[40:41], 0, v[132:133]
	s_mov_b32 m0, s48
	s_nop 0
	global_load_lds_dwordx4 v[218:219], off
	s_waitcnt vmcnt(9)
	s_waitcnt lgkmcnt(0)
	s_barrier
	s_setprio 1
	s_waitcnt lgkmcnt(0)
	v_mfma_i32_16x16x64_i8 v[124:127], v[140:143], v[180:183], v[124:127]
	v_mfma_i32_16x16x64_i8 v[120:123], v[148:151], v[180:183], v[120:123]
	v_mfma_i32_16x16x64_i8 v[116:119], v[140:143], v[188:191], v[116:119]
	v_mfma_i32_16x16x64_i8 v[112:115], v[148:151], v[188:191], v[112:115]
	v_mfma_i32_16x16x64_i8 v[104:107], v[140:143], v[196:199], v[104:107]
	v_mfma_i32_16x16x64_i8 v[96:99], v[148:151], v[196:199], v[96:99]
	v_mfma_i32_16x16x64_i8 v[88:91], v[140:143], v[204:207], v[88:91]
	v_mfma_i32_16x16x64_i8 v[80:83], v[148:151], v[204:207], v[80:83]
	v_mfma_i32_16x16x64_i8 v[124:127], v[144:147], v[184:187], v[124:127]
	v_mfma_i32_16x16x64_i8 v[120:123], v[152:155], v[184:187], v[120:123]
	v_mfma_i32_16x16x64_i8 v[116:119], v[144:147], v[192:195], v[116:119]
	v_mfma_i32_16x16x64_i8 v[112:115], v[152:155], v[192:195], v[112:115]
	v_mfma_i32_16x16x64_i8 v[104:107], v[144:147], v[200:203], v[104:107]
	v_mfma_i32_16x16x64_i8 v[96:99], v[152:155], v[200:203], v[96:99]
	v_mfma_i32_16x16x64_i8 v[88:91], v[144:147], v[208:211], v[88:91]
	v_mfma_i32_16x16x64_i8 v[80:83], v[152:155], v[208:211], v[80:83]
	s_setprio 0
	s_setprio 1
	v_mfma_i32_16x16x64_i8 v[108:111], v[156:159], v[180:183], v[108:111]
	v_mfma_i32_16x16x64_i8 v[100:103], v[164:167], v[180:183], v[100:103]
	v_mfma_i32_16x16x64_i8 v[92:95], v[156:159], v[188:191], v[92:95]
	v_mfma_i32_16x16x64_i8 v[84:87], v[164:167], v[188:191], v[84:87]
	v_mfma_i32_16x16x64_i8 v[76:79], v[156:159], v[196:199], v[76:79]
	v_mfma_i32_16x16x64_i8 v[72:75], v[164:167], v[196:199], v[72:75]
	v_mfma_i32_16x16x64_i8 v[68:71], v[156:159], v[204:207], v[68:71]
	v_mfma_i32_16x16x64_i8 v[64:67], v[164:167], v[204:207], v[64:67]
	v_mfma_i32_16x16x64_i8 v[108:111], v[160:163], v[184:187], v[108:111]
	v_mfma_i32_16x16x64_i8 v[100:103], v[168:171], v[184:187], v[100:103]
	v_mfma_i32_16x16x64_i8 v[92:95], v[160:163], v[192:195], v[92:95]
	v_mfma_i32_16x16x64_i8 v[84:87], v[168:171], v[192:195], v[84:87]
	v_mfma_i32_16x16x64_i8 v[76:79], v[160:163], v[200:203], v[76:79]
	v_mfma_i32_16x16x64_i8 v[72:75], v[168:171], v[200:203], v[72:75]
	v_mfma_i32_16x16x64_i8 v[68:71], v[160:163], v[208:211], v[68:71]
	v_mfma_i32_16x16x64_i8 v[64:67], v[168:171], v[208:211], v[64:67]
	s_setprio 0
	s_barrier
	s_add_i32 s40, s75, s42
	v_lshl_add_u64 v[172:173], v[172:173], 0, s[20:21]
	s_mov_b32 m0, s40
	ds_read_b128 v[180:183], v178 offset:49152
	ds_read_b128 v[184:187], v178 offset:50176
	ds_read_b128 v[188:191], v178 offset:51200
	ds_read_b128 v[192:195], v178 offset:52224
	ds_read_b128 v[196:199], v178 offset:53248
	ds_read_b128 v[200:203], v178 offset:54272
	ds_read_b128 v[204:207], v178 offset:55296
	ds_read_b128 v[208:211], v178 offset:56320
	global_load_lds_dwordx4 v[172:173], off
	s_add_i32 m0, s40, 0x2000
	s_add_u32 s38, s38, 0x80080
	v_lshl_add_u64 v[172:173], v[212:213], 0, s[20:21]
	s_addc_u32 s39, s39, 0
	s_add_i32 s40, s76, s42
	global_load_lds_dwordx4 v[172:173], off
	v_lshl_add_u64 v[172:173], s[38:39], 0, v[130:131]
	s_mov_b32 m0, s40
	s_nop 0
	global_load_lds_dwordx4 v[172:173], off
	v_lshl_add_u64 v[172:173], s[38:39], 0, v[134:135]
	s_add_i32 m0, s40, 0x2000
	s_nop 0
	global_load_lds_dwordx4 v[172:173], off
	v_lshl_add_u64 v[172:173], v[214:215], 0, s[20:21]
	s_mov_b32 m0, s51
	s_nop 0
	global_load_lds_dwordx4 v[172:173], off
	v_lshl_add_u64 v[172:173], v[216:217], 0, s[20:21]
	s_mov_b32 m0, s52
	s_nop 0
	global_load_lds_dwordx4 v[172:173], off
	s_waitcnt vmcnt(8)
	s_waitcnt lgkmcnt(0)
	s_barrier
	s_setprio 1
	s_waitcnt lgkmcnt(0)
	v_mfma_i32_16x16x64_i8 v[60:63], v[140:143], v[180:183], v[60:63]
	v_mfma_i32_16x16x64_i8 v[56:59], v[148:151], v[180:183], v[56:59]
	v_mfma_i32_16x16x64_i8 v[52:55], v[140:143], v[188:191], v[52:55]
	v_mfma_i32_16x16x64_i8 v[48:51], v[148:151], v[188:191], v[48:51]
	v_fmaak_f32 v226, v226, v220, 0x4b400000
	v_mfma_i32_16x16x64_i8 v[40:43], v[140:143], v[196:199], v[40:43]
	v_mfma_i32_16x16x64_i8 v[32:35], v[148:151], v[196:199], v[32:35]
	v_mfma_i32_16x16x64_i8 v[24:27], v[140:143], v[204:207], v[24:27]
	v_mfma_i32_16x16x64_i8 v[16:19], v[148:151], v[204:207], v[16:19]
	v_fmaak_f32 v227, v227, v225, 0x4b400000
	v_mfma_i32_16x16x64_i8 v[60:63], v[144:147], v[184:187], v[60:63]
	v_mfma_i32_16x16x64_i8 v[56:59], v[152:155], v[184:187], v[56:59]
	v_mfma_i32_16x16x64_i8 v[52:55], v[144:147], v[192:195], v[52:55]
	v_mfma_i32_16x16x64_i8 v[48:51], v[152:155], v[192:195], v[48:51]
	v_fmaak_f32 v228, v228, v252, 0x4b400000
	v_mfma_i32_16x16x64_i8 v[40:43], v[144:147], v[200:203], v[40:43]
	v_mfma_i32_16x16x64_i8 v[32:35], v[152:155], v[200:203], v[32:35]
	v_mfma_i32_16x16x64_i8 v[24:27], v[144:147], v[208:211], v[24:27]
	v_mfma_i32_16x16x64_i8 v[16:19], v[152:155], v[208:211], v[16:19]
	v_fmaak_f32 v229, v229, v253, 0x4b400000
	s_setprio 0
	s_setprio 1
	v_mfma_i32_16x16x64_i8 v[44:47], v[156:159], v[180:183], v[44:47]
	v_mfma_i32_16x16x64_i8 v[36:39], v[164:167], v[180:183], v[36:39]
	v_mfma_i32_16x16x64_i8 v[28:31], v[156:159], v[188:191], v[28:31]
	v_mfma_i32_16x16x64_i8 v[20:23], v[164:167], v[188:191], v[20:23]
	v_alignbit_b32 v239, v226, v239, 8
	v_mfma_i32_16x16x64_i8 v[12:15], v[156:159], v[196:199], v[12:15]
	v_mfma_i32_16x16x64_i8 v[8:11], v[164:167], v[196:199], v[8:11]
	v_mfma_i32_16x16x64_i8 v[4:7], v[156:159], v[204:207], v[4:7]
	v_mfma_i32_16x16x64_i8 v[0:3], v[164:167], v[204:207], v[0:3]
	v_alignbit_b32 v243, v227, v243, 8
	v_mfma_i32_16x16x64_i8 v[44:47], v[160:163], v[184:187], v[44:47]
	v_mfma_i32_16x16x64_i8 v[36:39], v[168:171], v[184:187], v[36:39]
	v_mfma_i32_16x16x64_i8 v[28:31], v[160:163], v[192:195], v[28:31]
	v_mfma_i32_16x16x64_i8 v[20:23], v[168:171], v[192:195], v[20:23]
	v_alignbit_b32 v247, v228, v247, 8
	v_mfma_i32_16x16x64_i8 v[12:15], v[160:163], v[200:203], v[12:15]
	v_mfma_i32_16x16x64_i8 v[8:11], v[168:171], v[200:203], v[8:11]
	v_mfma_i32_16x16x64_i8 v[4:7], v[160:163], v[208:211], v[4:7]
	v_mfma_i32_16x16x64_i8 v[0:3], v[168:171], v[208:211], v[0:3]
	v_alignbit_b32 v251, v229, v251, 8
	s_setprio 0
	s_barrier
	s_and_b32 s77, s84, 3
	s_cbranch_scc0 .Lq_mv_L
.Lq_mvx_L:
	s_add_u32 s36, s36, 0x100
	s_addc_u32 s37, s37, 0
	s_add_u32 s72, s72, 0x100
	s_addc_u32 s73, s73, 0
	s_cmp_ge_i32 s74, s8
	s_mov_b32 s38, s74
	s_cbranch_scc1 .Lq_epi
	s_cmp_eq_u32 s32, 1
	s_cbranch_scc1 .Lq_body_L
	s_cmp_eq_u32 s32, 2
	s_cbranch_scc1 .Lq_body_ST
	s_branch .LBB0_1238
.Lq_mv_L:
	s_bfe_u32 s77, s84, 0x20002
	s_cmp_eq_u32 s77, 1
	s_cbranch_scc1 .Lq_mv0_L
	s_cmp_eq_u32 s77, 2
	s_cbranch_scc1 .Lq_mv1_L
	s_cmp_eq_u32 s77, 3
	s_cbranch_scc1 .Lq_mv2_L
	s_mov_b32 s32, 2
	s_branch .Lq_mvx_L
.Lq_mv0_L:
	v_mov_b32_e32 v236, v239
	v_mov_b32_e32 v240, v243
	v_mov_b32_e32 v244, v247
	v_mov_b32_e32 v248, v251
	s_branch .Lq_mvx_L
.Lq_mv1_L:
	v_mov_b32_e32 v237, v239
	v_mov_b32_e32 v241, v243
	v_mov_b32_e32 v245, v247
	v_mov_b32_e32 v249, v251
	s_branch .Lq_mvx_L
.Lq_mv2_L:
	v_mov_b32_e32 v238, v239
	v_mov_b32_e32 v242, v243
	v_mov_b32_e32 v246, v247
	v_mov_b32_e32 v250, v251
	s_branch .Lq_mvx_L
.Lq_body_ST:
	s_add_i32 s74, s38, 2
	s_add_u32 s39, s36, 0xfff80080
	s_addc_u32 s40, s37, -1
	s_cmp_eq_u32 s71, s38
	s_cselect_b32 s41, s67, s40
	s_cselect_b32 s40, s68, s39
	v_add_u32_e32 v152, s55, v177
	v_add_u32_e32 v168, s60, v177
	ds_read_b128 v[140:143], v152
	ds_read_b128 v[144:147], v152 offset:1024
	ds_read_b128 v[148:151], v152 offset:2048
	ds_read_b128 v[152:155], v152 offset:3072
	ds_read_b128 v[156:159], v168
	ds_read_b128 v[160:163], v168 offset:1024
	ds_read_b128 v[164:167], v168 offset:2048
	ds_read_b128 v[168:171], v168 offset:3072
	s_cselect_b32 s38, s70, s72
	s_cselect_b32 s39, s69, s73
	v_lshl_add_u64 v[172:173], s[36:37], 0, v[136:137]
	s_add_i32 m0, s45, 0xc000
	ds_read_b128 v[180:183], v178
	ds_read_b128 v[184:187], v178 offset:1024
	ds_read_b128 v[188:191], v178 offset:2048
	ds_read_b128 v[192:195], v178 offset:3072
	ds_read_b128 v[196:199], v178 offset:4096
	ds_read_b128 v[200:203], v178 offset:5120
	ds_read_b128 v[204:207], v178 offset:6144
	ds_read_b128 v[208:211], v178 offset:7168
	global_load_lds_dwordx4 v[172:173], off
	v_lshl_add_u64 v[172:173], s[36:37], 0, v[138:139]
	s_add_i32 m0, s45, 0xe000
	s_nop 0
	global_load_lds_dwordx4 v[172:173], off
	global_store_dwordx4 v224, v[236:239], s[98:99]
	s_add_u32 s98, s98, 0x2b00
	s_addc_u32 s99, s99, 0
	global_store_dwordx4 v224, v[240:243], s[98:99]
	s_add_u32 s98, s98, 0x2b00
	s_addc_u32 s99, s99, 0
	global_store_dwordx4 v224, v[244:247], s[98:99]
	s_add_u32 s98, s98, 0x2b00
	s_addc_u32 s99, s99, 0
	global_store_dwordx4 v224, v[248:251], s[98:99]
	s_cmp_lt_u32 s84, s87
	s_cbranch_scc0 .Lq_st_last
	s_lshr_b32 s76, s84, 4
	s_lshr_b32 s77, s76, 1
	s_mul_i32 s77, s77, 0x17d07
	s_lshr_b32 s77, s77, 22
	s_cmp_lg_u32 s77, s89
	s_cbranch_scc1 .Lq_newnb_ST
.Lq_nbok_ST:
	s_mul_i32 s75, s77, 86
	s_sub_u32 s76, s76, s75
	s_lshl_b32 s76, s76, 7
	s_mul_i32 s98, s77, 0x56000
	s_add_u32 s98, s98, s76
	s_add_u32 s98, s96, s98
	s_addc_u32 s99, s97, 0
	s_and_b32 s75, s84, 15
	s_add_u32 s76, s76, s75
	s_lshl_b32 s76, s76, 14
	s_lshl_b32 s77, s77, 7
	s_add_u32 s76, s76, s77
	s_load_dwordx2 s[100:101], s[0:1], 0x88
	s_waitcnt lgkmcnt(0)
	s_add_u32 s100, s100, s76
	s_addc_u32 s101, s101, 0
	global_load_dwordx4 v[226:229], v223, s[100:101] nt
	s_add_u32 s100, s100, 0x4000
	s_addc_u32 s101, s101, 0
	s_add_u32 s84, s84, 1
	s_mov_b32 s32, 1
	s_branch .Lq_st_j
.Lq_st_last:
	global_load_dword v226, v223, s[96:97]
	s_mov_b32 s32, 0
.Lq_st_j:
	s_waitcnt vmcnt(13)
	s_waitcnt lgkmcnt(0)
	s_barrier
	s_setprio 1
	s_waitcnt lgkmcnt(0)
	v_mfma_i32_16x16x64_i8 v[124:127], v[140:143], v[180:183], v[124:127]
	v_mfma_i32_16x16x64_i8 v[120:123], v[148:151], v[180:183], v[120:123]
	v_mfma_i32_16x16x64_i8 v[116:119], v[140:143], v[188:191], v[116:119]
	v_mfma_i32_16x16x64_i8 v[112:115], v[148:151], v[188:191], v[112:115]
	v_mfma_i32_16x16x64_i8 v[104:107], v[140:143], v[196:199], v[104:107]
	v_mfma_i32_16x16x64_i8 v[96:99], v[148:151], v[196:199], v[96:99]
	v_mfma_i32_16x16x64_i8 v[88:91], v[140:143], v[204:207], v[88:91]
	v_mfma_i32_16x16x64_i8 v[80:83], v[148:151], v[204:207], v[80:83]
	v_mfma_i32_16x16x64_i8 v[124:127], v[144:147], v[184:187], v[124:127]
	v_mfma_i32_16x16x64_i8 v[120:123], v[152:155], v[184:187], v[120:123]
	v_mfma_i32_16x16x64_i8 v[116:119], v[144:147], v[192:195], v[116:119]
	v_mfma_i32_16x16x64_i8 v[112:115], v[152:155], v[192:195], v[112:115]
	v_mfma_i32_16x16x64_i8 v[104:107], v[144:147], v[200:203], v[104:107]
	v_mfma_i32_16x16x64_i8 v[96:99], v[152:155], v[200:203], v[96:99]
	v_mfma_i32_16x16x64_i8 v[88:91], v[144:147], v[208:211], v[88:91]
	v_mfma_i32_16x16x64_i8 v[80:83], v[152:155], v[208:211], v[80:83]
	s_setprio 0
	s_setprio 1
	v_mfma_i32_16x16x64_i8 v[108:111], v[156:159], v[180:183], v[108:111]
	v_mfma_i32_16x16x64_i8 v[100:103], v[164:167], v[180:183], v[100:103]
	v_mfma_i32_16x16x64_i8 v[92:95], v[156:159], v[188:191], v[92:95]
	v_mfma_i32_16x16x64_i8 v[84:87], v[164:167], v[188:191], v[84:87]
	v_mfma_i32_16x16x64_i8 v[76:79], v[156:159], v[196:199], v[76:79]
	v_mfma_i32_16x16x64_i8 v[72:75], v[164:167], v[196:199], v[72:75]
	v_mfma_i32_16x16x64_i8 v[68:71], v[156:159], v[204:207], v[68:71]
	v_mfma_i32_16x16x64_i8 v[64:67], v[164:167], v[204:207], v[64:67]
	v_mfma_i32_16x16x64_i8 v[108:111], v[160:163], v[184:187], v[108:111]
	v_mfma_i32_16x16x64_i8 v[100:103], v[168:171], v[184:187], v[100:103]
	v_mfma_i32_16x16x64_i8 v[92:95], v[160:163], v[192:195], v[92:95]
	v_mfma_i32_16x16x64_i8 v[84:87], v[168:171], v[192:195], v[84:87]
	v_mfma_i32_16x16x64_i8 v[76:79], v[160:163], v[200:203], v[76:79]
	v_mfma_i32_16x16x64_i8 v[72:75], v[168:171], v[200:203], v[72:75]
	v_mfma_i32_16x16x64_i8 v[68:71], v[160:163], v[208:211], v[68:71]
	v_mfma_i32_16x16x64_i8 v[64:67], v[168:171], v[208:211], v[64:67]
	s_setprio 0
	s_barrier
	s_add_i32 s75, s55, s42
	v_lshl_add_u64 v[172:173], s[38:39], 0, v[130:131]
	s_mov_b32 m0, s75
	ds_read_b128 v[180:183], v178 offset:16384
	ds_read_b128 v[184:187], v178 offset:17408
	ds_read_b128 v[188:191], v178 offset:18432
	ds_read_b128 v[192:195], v178 offset:19456
	ds_read_b128 v[196:199], v178 offset:20480
	ds_read_b128 v[200:203], v178 offset:21504
	ds_read_b128 v[204:207], v178 offset:22528
	ds_read_b128 v[208:211], v178 offset:23552
	global_load_lds_dwordx4 v[172:173], off
	s_add_i32 m0, s75, 0x2000
	s_add_u32 s76, s38, 0x80000
	v_lshl_add_u64 v[212:213], s[38:39], 0, v[134:135]
	s_addc_u32 s77, s39, 0
	s_add_i32 s75, s60, s42
	global_load_lds_dwordx4 v[212:213], off
	v_lshl_add_u64 v[214:215], s[76:77], 0, v[130:131]
	s_mov_b32 m0, s75
	v_lshl_add_u64 v[216:217], s[40:41], 0, v[132:133]
	global_load_lds_dwordx4 v[214:215], off
	v_lshl_add_u64 v[214:215], s[76:77], 0, v[134:135]
	s_add_i32 m0, s75, 0x2000
	s_nop 0
	global_load_lds_dwordx4 v[214:215], off
	v_lshl_add_u64 v[214:215], s[40:41], 0, v[128:129]
	s_mov_b32 m0, s45
	s_nop 0
	global_load_lds_dwordx4 v[214:215], off
	s_mov_b32 m0, s46
	s_nop 0
	global_load_lds_dwordx4 v[216:217], off
	s_waitcnt vmcnt(13)
	s_waitcnt lgkmcnt(0)
	s_barrier
	s_setprio 1
	s_waitcnt lgkmcnt(0)
	v_mfma_i32_16x16x64_i8 v[60:63], v[140:143], v[180:183], v[60:63]
	v_mfma_i32_16x16x64_i8 v[56:59], v[148:151], v[180:183], v[56:59]
	v_mfma_i32_16x16x64_i8 v[52:55], v[140:143], v[188:191], v[52:55]
	v_mfma_i32_16x16x64_i8 v[48:51], v[148:151], v[188:191], v[48:51]
	v_mfma_i32_16x16x64_i8 v[40:43], v[140:143], v[196:199], v[40:43]
	v_mfma_i32_16x16x64_i8 v[32:35], v[148:151], v[196:199], v[32:35]
	v_mfma_i32_16x16x64_i8 v[24:27], v[140:143], v[204:207], v[24:27]
	v_mfma_i32_16x16x64_i8 v[16:19], v[148:151], v[204:207], v[16:19]
	v_mfma_i32_16x16x64_i8 v[60:63], v[144:147], v[184:187], v[60:63]
	v_mfma_i32_16x16x64_i8 v[56:59], v[152:155], v[184:187], v[56:59]
	v_mfma_i32_16x16x64_i8 v[52:55], v[144:147], v[192:195], v[52:55]
	v_mfma_i32_16x16x64_i8 v[48:51], v[152:155], v[192:195], v[48:51]
	v_mfma_i32_16x16x64_i8 v[40:43], v[144:147], v[200:203], v[40:43]
	v_mfma_i32_16x16x64_i8 v[32:35], v[152:155], v[200:203], v[32:35]
	v_mfma_i32_16x16x64_i8 v[24:27], v[144:147], v[208:211], v[24:27]
	v_mfma_i32_16x16x64_i8 v[16:19], v[152:155], v[208:211], v[16:19]
	s_setprio 0
	s_setprio 1
	v_mfma_i32_16x16x64_i8 v[44:47], v[156:159], v[180:183], v[44:47]
	v_mfma_i32_16x16x64_i8 v[36:39], v[164:167], v[180:183], v[36:39]
	v_mfma_i32_16x16x64_i8 v[28:31], v[156:159], v[188:191], v[28:31]
	v_mfma_i32_16x16x64_i8 v[20:23], v[164:167], v[188:191], v[20:23]
	v_mfma_i32_16x16x64_i8 v[12:15], v[156:159], v[196:199], v[12:15]
	v_mfma_i32_16x16x64_i8 v[8:11], v[164:167], v[196:199], v[8:11]
	v_mfma_i32_16x16x64_i8 v[4:7], v[156:159], v[204:207], v[4:7]
	v_mfma_i32_16x16x64_i8 v[0:3], v[164:167], v[204:207], v[0:3]
	v_mfma_i32_16x16x64_i8 v[44:47], v[160:163], v[184:187], v[44:47]
	v_mfma_i32_16x16x64_i8 v[36:39], v[168:171], v[184:187], v[36:39]
	v_mfma_i32_16x16x64_i8 v[28:31], v[160:163], v[192:195], v[28:31]
	v_mfma_i32_16x16x64_i8 v[20:23], v[168:171], v[192:195], v[20:23]
	v_mfma_i32_16x16x64_i8 v[12:15], v[160:163], v[200:203], v[12:15]
	v_mfma_i32_16x16x64_i8 v[8:11], v[168:171], v[200:203], v[8:11]
	v_mfma_i32_16x16x64_i8 v[4:7], v[160:163], v[208:211], v[4:7]
	v_mfma_i32_16x16x64_i8 v[0:3], v[168:171], v[208:211], v[0:3]
	s_setprio 0
	s_barrier
	s_add_i32 s75, 0, 0x18000
	s_add_i32 s76, 0, 0x1c000
	v_add_u32_e32 v152, s75, v177
	v_add_u32_e32 v168, s76, v177
	ds_read_b128 v[140:143], v152
	ds_read_b128 v[144:147], v152 offset:1024
	ds_read_b128 v[148:151], v152 offset:2048
	ds_read_b128 v[152:155], v152 offset:3072
	ds_read_b128 v[156:159], v168
	ds_read_b128 v[160:163], v168 offset:1024
	ds_read_b128 v[164:167], v168 offset:2048
	ds_read_b128 v[168:171], v168 offset:3072
	s_add_u32 s40, s40, 0x80000
	s_addc_u32 s41, s41, 0
	s_mov_b32 m0, s47
	v_lshl_add_u64 v[218:219], s[40:41], 0, v[128:129]
	ds_read_b128 v[180:183], v178 offset:32768
	ds_read_b128 v[184:187], v178 offset:33792
	ds_read_b128 v[188:191], v178 offset:34816
	ds_read_b128 v[192:195], v178 offset:35840
	ds_read_b128 v[196:199], v178 offset:36864
	ds_read_b128 v[200:203], v178 offset:37888
	ds_read_b128 v[204:207], v178 offset:38912
	ds_read_b128 v[208:211], v178 offset:39936
	global_load_lds_dwordx4 v[218:219], off
	v_lshl_add_u64 v[218:219], s[40:41], 0, v[132:133]
	s_mov_b32 m0, s48
	s_nop 0
	global_load_lds_dwordx4 v[218:219], off
	s_waitcnt vmcnt(13)
	s_waitcnt lgkmcnt(0)
	s_barrier
	s_setprio 1
	s_waitcnt lgkmcnt(0)
	v_mfma_i32_16x16x64_i8 v[124:127], v[140:143], v[180:183], v[124:127]
	v_mfma_i32_16x16x64_i8 v[120:123], v[148:151], v[180:183], v[120:123]
	v_mfma_i32_16x16x64_i8 v[116:119], v[140:143], v[188:191], v[116:119]
	v_mfma_i32_16x16x64_i8 v[112:115], v[148:151], v[188:191], v[112:115]
	v_mfma_i32_16x16x64_i8 v[104:107], v[140:143], v[196:199], v[104:107]
	v_mfma_i32_16x16x64_i8 v[96:99], v[148:151], v[196:199], v[96:99]
	v_mfma_i32_16x16x64_i8 v[88:91], v[140:143], v[204:207], v[88:91]
	v_mfma_i32_16x16x64_i8 v[80:83], v[148:151], v[204:207], v[80:83]
	v_mfma_i32_16x16x64_i8 v[124:127], v[144:147], v[184:187], v[124:127]
	v_mfma_i32_16x16x64_i8 v[120:123], v[152:155], v[184:187], v[120:123]
	v_mfma_i32_16x16x64_i8 v[116:119], v[144:147], v[192:195], v[116:119]
	v_mfma_i32_16x16x64_i8 v[112:115], v[152:155], v[192:195], v[112:115]
	v_mfma_i32_16x16x64_i8 v[104:107], v[144:147], v[200:203], v[104:107]
	v_mfma_i32_16x16x64_i8 v[96:99], v[152:155], v[200:203], v[96:99]
	v_mfma_i32_16x16x64_i8 v[88:91], v[144:147], v[208:211], v[88:91]
	v_mfma_i32_16x16x64_i8 v[80:83], v[152:155], v[208:211], v[80:83]
	s_setprio 0
	s_setprio 1
	v_mfma_i32_16x16x64_i8 v[108:111], v[156:159], v[180:183], v[108:111]
	v_mfma_i32_16x16x64_i8 v[100:103], v[164:167], v[180:183], v[100:103]
	v_mfma_i32_16x16x64_i8 v[92:95], v[156:159], v[188:191], v[92:95]
	v_mfma_i32_16x16x64_i8 v[84:87], v[164:167], v[188:191], v[84:87]
	v_mfma_i32_16x16x64_i8 v[76:79], v[156:159], v[196:199], v[76:79]
	v_mfma_i32_16x16x64_i8 v[72:75], v[164:167], v[196:199], v[72:75]
	v_mfma_i32_16x16x64_i8 v[68:71], v[156:159], v[204:207], v[68:71]
	v_mfma_i32_16x16x64_i8 v[64:67], v[164:167], v[204:207], v[64:67]
	v_mfma_i32_16x16x64_i8 v[108:111], v[160:163], v[184:187], v[108:111]
	v_mfma_i32_16x16x64_i8 v[100:103], v[168:171], v[184:187], v[100:103]
	v_mfma_i32_16x16x64_i8 v[92:95], v[160:163], v[192:195], v[92:95]
	v_mfma_i32_16x16x64_i8 v[84:87], v[168:171], v[192:195], v[84:87]
	v_mfma_i32_16x16x64_i8 v[76:79], v[160:163], v[200:203], v[76:79]
	v_mfma_i32_16x16x64_i8 v[72:75], v[168:171], v[200:203], v[72:75]
	v_mfma_i32_16x16x64_i8 v[68:71], v[160:163], v[208:211], v[68:71]
	v_mfma_i32_16x16x64_i8 v[64:67], v[168:171], v[208:211], v[64:67]
	s_setprio 0
	s_barrier
	s_add_i32 s40, s75, s42
	v_lshl_add_u64 v[172:173], v[172:173], 0, s[20:21]
	s_mov_b32 m0, s40
	ds_read_b128 v[180:183], v178 offset:49152
	ds_read_b128 v[184:187], v178 offset:50176
	ds_read_b128 v[188:191], v178 offset:51200
	ds_read_b128 v[192:195], v178 offset:52224
	ds_read_b128 v[196:199], v178 offset:53248
	ds_read_b128 v[200:203], v178 offset:54272
	ds_read_b128 v[204:207], v178 offset:55296
	ds_read_b128 v[208:211], v178 offset:56320
	global_load_lds_dwordx4 v[172:173], off
	s_add_i32 m0, s40, 0x2000
	s_add_u32 s38, s38, 0x80080
	v_lshl_add_u64 v[172:173], v[212:213], 0, s[20:21]
	s_addc_u32 s39, s39, 0
	s_add_i32 s40, s76, s42
	global_load_lds_dwordx4 v[172:173], off
	v_lshl_add_u64 v[172:173], s[38:39], 0, v[130:131]
	s_mov_b32 m0, s40
	s_nop 0
	global_load_lds_dwordx4 v[172:173], off
	v_lshl_add_u64 v[172:173], s[38:39], 0, v[134:135]
	s_add_i32 m0, s40, 0x2000
	s_nop 0
	global_load_lds_dwordx4 v[172:173], off
	v_lshl_add_u64 v[172:173], v[214:215], 0, s[20:21]
	s_mov_b32 m0, s51
	s_nop 0
	global_load_lds_dwordx4 v[172:173], off
	v_lshl_add_u64 v[172:173], v[216:217], 0, s[20:21]
	s_mov_b32 m0, s52
	s_nop 0
	global_load_lds_dwordx4 v[172:173], off
	s_waitcnt vmcnt(8)
	s_waitcnt lgkmcnt(0)
	s_barrier
	s_setprio 1
	s_waitcnt lgkmcnt(0)
	v_mfma_i32_16x16x64_i8 v[60:63], v[140:143], v[180:183], v[60:63]
	v_mfma_i32_16x16x64_i8 v[56:59], v[148:151], v[180:183], v[56:59]
	v_mfma_i32_16x16x64_i8 v[52:55], v[140:143], v[188:191], v[52:55]
	v_mfma_i32_16x16x64_i8 v[48:51], v[148:151], v[188:191], v[48:51]
	v_fmaak_f32 v226, v226, v220, 0x4b400000
	v_mfma_i32_16x16x64_i8 v[40:43], v[140:143], v[196:199], v[40:43]
	v_mfma_i32_16x16x64_i8 v[32:35], v[148:151], v[196:199], v[32:35]
	v_mfma_i32_16x16x64_i8 v[24:27], v[140:143], v[204:207], v[24:27]
	v_mfma_i32_16x16x64_i8 v[16:19], v[148:151], v[204:207], v[16:19]
	v_fmaak_f32 v227, v227, v225, 0x4b400000
	v_mfma_i32_16x16x64_i8 v[60:63], v[144:147], v[184:187], v[60:63]
	v_mfma_i32_16x16x64_i8 v[56:59], v[152:155], v[184:187], v[56:59]
	v_mfma_i32_16x16x64_i8 v[52:55], v[144:147], v[192:195], v[52:55]
	v_mfma_i32_16x16x64_i8 v[48:51], v[152:155], v[192:195], v[48:51]
	v_fmaak_f32 v228, v228, v252, 0x4b400000
	v_mfma_i32_16x16x64_i8 v[40:43], v[144:147], v[200:203], v[40:43]
	v_mfma_i32_16x16x64_i8 v[32:35], v[152:155], v[200:203], v[32:35]
	v_mfma_i32_16x16x64_i8 v[24:27], v[144:147], v[208:211], v[24:27]
	v_mfma_i32_16x16x64_i8 v[16:19], v[152:155], v[208:211], v[16:19]
	v_fmaak_f32 v229, v229, v253, 0x4b400000
	s_setprio 0
	s_setprio 1
	v_mfma_i32_16x16x64_i8 v[44:47], v[156:159], v[180:183], v[44:47]
	v_mfma_i32_16x16x64_i8 v[36:39], v[164:167], v[180:183], v[36:39]
	v_mfma_i32_16x16x64_i8 v[28:31], v[156:159], v[188:191], v[28:31]
	v_mfma_i32_16x16x64_i8 v[20:23], v[164:167], v[188:191], v[20:23]
	v_alignbit_b32 v239, v226, v239, 8
	v_mfma_i32_16x16x64_i8 v[12:15], v[156:159], v[196:199], v[12:15]
	v_mfma_i32_16x16x64_i8 v[8:11], v[164:167], v[196:199], v[8:11]
	v_mfma_i32_16x16x64_i8 v[4:7], v[156:159], v[204:207], v[4:7]
	v_mfma_i32_16x16x64_i8 v[0:3], v[164:167], v[204:207], v[0:3]
	v_alignbit_b32 v243, v227, v243, 8
	v_mfma_i32_16x16x64_i8 v[44:47], v[160:163], v[184:187], v[44:47]
	v_mfma_i32_16x16x64_i8 v[36:39], v[168:171], v[184:187], v[36:39]
	v_mfma_i32_16x16x64_i8 v[28:31], v[160:163], v[192:195], v[28:31]
	v_mfma_i32_16x16x64_i8 v[20:23], v[168:171], v[192:195], v[20:23]
	v_alignbit_b32 v247, v228, v247, 8
	v_mfma_i32_16x16x64_i8 v[12:15], v[160:163], v[200:203], v[12:15]
	v_mfma_i32_16x16x64_i8 v[8:11], v[168:171], v[200:203], v[8:11]
	v_mfma_i32_16x16x64_i8 v[4:7], v[160:163], v[208:211], v[4:7]
	v_mfma_i32_16x16x64_i8 v[0:3], v[168:171], v[208:211], v[0:3]
	v_alignbit_b32 v251, v229, v251, 8
	s_setprio 0
	s_barrier
	s_cmp_eq_u32 s32, 0
	s_cbranch_scc1 .Lq_mvx_ST
	s_and_b32 s77, s84, 3
	s_cbranch_scc0 .Lq_mv_ST

.Lq_newnb_ST:
	s_mov_b32 s89, s77
	s_lshl_b32 s75, s77, 7
	s_add_u32 s75, s75, 0xc0000
	v_and_b32_e32 v240, 0x70, v223
	v_add_u32_e32 v240, s75, v240
	global_load_dwordx4 v[240:243], v240, s[96:97]
	s_waitcnt vmcnt(0)
	s_mov_b32 s75, 0x42fe0000
	v_div_scale_f32 v236, vcc, v240, v240, s75
	v_rcp_f32_e32 v237, v236
	s_nop 1
	v_fma_f32 v238, -v236, v237, 1.0
	v_fmac_f32_e32 v237, v238, v237
	v_div_scale_f32 v238, vcc, s75, v240, s75
	v_mul_f32_e32 v239, v238, v237
	v_fma_f32 v244, -v236, v239, v238
	v_fmac_f32_e32 v239, v244, v237
	v_fma_f32 v236, -v236, v239, v238
	s_nop 4
	v_div_fmas_f32 v236, v236, v237, v239
	v_div_fixup_f32 v236, v236, v240, s75
	v_cmp_lt_f32_e32 vcc, 0, v240
	s_nop 1
	v_cndmask_b32_e32 v220, 0, v236, vcc
	v_div_scale_f32 v236, vcc, v241, v241, s75
	v_rcp_f32_e32 v237, v236
	s_nop 1
	v_fma_f32 v238, -v236, v237, 1.0
	v_fmac_f32_e32 v237, v238, v237
	v_div_scale_f32 v238, vcc, s75, v241, s75
	v_mul_f32_e32 v239, v238, v237
	v_fma_f32 v244, -v236, v239, v238
	v_fmac_f32_e32 v239, v244, v237
	v_fma_f32 v236, -v236, v239, v238
	s_nop 4
	v_div_fmas_f32 v236, v236, v237, v239
	v_div_fixup_f32 v236, v236, v241, s75
	v_cmp_lt_f32_e32 vcc, 0, v241
	s_nop 1
	v_cndmask_b32_e32 v225, 0, v236, vcc
	v_div_scale_f32 v236, vcc, v242, v242, s75
	v_rcp_f32_e32 v237, v236
	s_nop 1
	v_fma_f32 v238, -v236, v237, 1.0
	v_fmac_f32_e32 v237, v238, v237
	v_div_scale_f32 v238, vcc, s75, v242, s75
	v_mul_f32_e32 v239, v238, v237
	v_fma_f32 v244, -v236, v239, v238
	v_fmac_f32_e32 v239, v244, v237
	v_fma_f32 v236, -v236, v239, v238
	s_nop 4
	v_div_fmas_f32 v236, v236, v237, v239
	v_div_fixup_f32 v236, v236, v242, s75
	v_cmp_lt_f32_e32 vcc, 0, v242
	s_nop 1
	v_cndmask_b32_e32 v252, 0, v236, vcc
	v_div_scale_f32 v236, vcc, v243, v243, s75
	v_rcp_f32_e32 v237, v236
	s_nop 1
	v_fma_f32 v238, -v236, v237, 1.0
	v_fmac_f32_e32 v237, v238, v237
	v_div_scale_f32 v238, vcc, s75, v243, s75
	v_mul_f32_e32 v239, v238, v237
	v_fma_f32 v244, -v236, v239, v238
	v_fmac_f32_e32 v239, v244, v237
	v_fma_f32 v236, -v236, v239, v238
	s_nop 4
	v_div_fmas_f32 v236, v236, v237, v239
	v_div_fixup_f32 v236, v236, v243, s75
	v_cmp_lt_f32_e32 vcc, 0, v243
	s_nop 1
	v_cndmask_b32_e32 v253, 0, v236, vcc
	s_branch .Lq_nbok_ST

.LBB0_1250:
.Lq_tail:
	s_cmp_eq_u32 s32, 2
	s_cbranch_scc0 .Lq_t_nost
	global_store_dwordx4 v224, v[236:239], s[98:99]
	s_add_u32 s98, s98, 0x2b00
	s_addc_u32 s99, s99, 0
	global_store_dwordx4 v224, v[240:243], s[98:99]
	s_add_u32 s98, s98, 0x2b00
	s_addc_u32 s99, s99, 0
	global_store_dwordx4 v224, v[244:247], s[98:99]
	s_add_u32 s98, s98, 0x2b00
	s_addc_u32 s99, s99, 0
	global_store_dwordx4 v224, v[248:251], s[98:99]
.Lq_t_nost:
	s_mov_b32 s32, 0
	s_cmp_lt_u32 s84, s87
	s_cbranch_scc0 .Lq_tail_done
	s_lshr_b32 s76, s84, 4
	s_lshr_b32 s77, s76, 1
	s_mul_i32 s77, s77, 0x17d07
	s_lshr_b32 s77, s77, 22
	s_cmp_lg_u32 s77, s89
	s_cbranch_scc1 .Lq_newnb_t
.Lq_nbok_t:
	s_mul_i32 s75, s77, 86
	s_sub_u32 s76, s76, s75
	s_lshl_b32 s76, s76, 7
	s_mul_i32 s98, s77, 0x56000
	s_add_u32 s98, s98, s76
	s_add_u32 s98, s96, s98
	s_addc_u32 s99, s97, 0
	s_and_b32 s75, s84, 15
	s_add_u32 s76, s76, s75
	s_lshl_b32 s76, s76, 14
	s_lshl_b32 s77, s77, 7
	s_add_u32 s76, s76, s77
	s_load_dwordx2 s[100:101], s[0:1], 0x88
	s_waitcnt lgkmcnt(0)
	s_add_u32 s100, s100, s76
	s_addc_u32 s101, s101, 0
	global_load_dwordx4 v[226:229], v223, s[100:101] nt
	s_add_u32 s100, s100, 0x4000
	s_addc_u32 s101, s101, 0
	s_add_u32 s84, s84, 1
	s_waitcnt vmcnt(0)
	v_fmaak_f32 v226, v226, v220, 0x4b400000
	v_fmaak_f32 v227, v227, v225, 0x4b400000
	v_fmaak_f32 v228, v228, v252, 0x4b400000
	v_fmaak_f32 v229, v229, v253, 0x4b400000
	v_alignbit_b32 v239, v226, v239, 8
	v_alignbit_b32 v243, v227, v243, 8
	v_alignbit_b32 v247, v228, v247, 8
	v_alignbit_b32 v251, v229, v251, 8
	s_and_b32 s77, s84, 3
	s_cbranch_scc0 .Lq_mv_t

.LBB0_1372:
	s_load_dwordx2 s[14:15], s[0:1], 0x88
	s_waitcnt lgkmcnt(0)
	s_cmpk_gt_i32 s86, 0x2aff
	s_branch .LBB0_1375

	.amdhsa_kernel _Z9hymba_fwd4Args
		.amdhsa_group_segment_fixed_size 0
		.amdhsa_private_segment_fixed_size 0
		.amdhsa_kernarg_size 432
		.amdhsa_user_sgpr_count 2
		.amdhsa_user_sgpr_dispatch_ptr 0
		.amdhsa_user_sgpr_queue_ptr 0
		.amdhsa_user_sgpr_kernarg_segment_ptr 1
		.amdhsa_user_sgpr_dispatch_id 0
		.amdhsa_user_sgpr_kernarg_preload_length 0
		.amdhsa_user_sgpr_kernarg_preload_offset 0
		.amdhsa_user_sgpr_private_segment_size 0
		.amdhsa_uses_dynamic_stack 0
		.amdhsa_enable_private_segment 0
		.amdhsa_system_sgpr_workgroup_id_x 1
		.amdhsa_system_sgpr_workgroup_id_y 0
		.amdhsa_system_sgpr_workgroup_id_z 0
		.amdhsa_system_sgpr_workgroup_info 0
		.amdhsa_system_vgpr_workitem_id 0
		.amdhsa_next_free_vgpr 256
		.amdhsa_next_free_sgpr 102
		.amdhsa_accum_offset 256
		.amdhsa_reserve_vcc 1
		.amdhsa_float_round_mode_32 0
		.amdhsa_float_round_mode_16_64 0
		.amdhsa_float_denorm_mode_32 3
		.amdhsa_float_denorm_mode_16_64 3
		.amdhsa_dx10_clamp 1
		.amdhsa_ieee_mode 1
		.amdhsa_fp16_overflow 0
		.amdhsa_tg_split 0
		.amdhsa_exception_fp_ieee_invalid_op 0
		.amdhsa_exception_fp_denorm_src 0
		.amdhsa_exception_fp_ieee_div_zero 0
		.amdhsa_exception_fp_ieee_overflow 0
		.amdhsa_exception_fp_ieee_underflow 0
		.amdhsa_exception_fp_ieee_inexact 0
		.amdhsa_exception_int_div_zero 0
	.end_amdhsa_kernel

amdhsa.kernels:
  - .agpr_count:     0
    .args:
      - .offset:         0
        .size:           176
        .value_kind:     by_value
      - .offset:         176
        .size:           4
        .value_kind:     hidden_block_count_x
      - .offset:         180
        .size:           4
        .value_kind:     hidden_block_count_y
      - .offset:         184
        .size:           4
        .value_kind:     hidden_block_count_z
      - .offset:         188
        .size:           2
        .value_kind:     hidden_group_size_x
      - .offset:         190
        .size:           2
        .value_kind:     hidden_group_size_y
      - .offset:         192
        .size:           2
        .value_kind:     hidden_group_size_z
      - .offset:         194
        .size:           2
        .value_kind:     hidden_remainder_x
      - .offset:         196
        .size:           2
        .value_kind:     hidden_remainder_y
      - .offset:         198
        .size:           2
        .value_kind:     hidden_remainder_z
      - .offset:         216
        .size:           8
        .value_kind:     hidden_global_offset_x
      - .offset:         224
        .size:           8
        .value_kind:     hidden_global_offset_y
      - .offset:         232
        .size:           8
        .value_kind:     hidden_global_offset_z
      - .offset:         240
        .size:           2
        .value_kind:     hidden_grid_dims
      - .offset:         296
        .size:           4
        .value_kind:     hidden_dynamic_lds_size
    .group_segment_fixed_size: 0
    .kernarg_segment_align: 8
    .kernarg_segment_size: 432
    .language:       OpenCL C
    .language_version:
      - 2
      - 0
    .max_flat_workgroup_size: 512
    .name:           _Z9hymba_fwd4Args
    .private_segment_fixed_size: 0
    .sgpr_count:     108
    .sgpr_spill_count: 90
    .symbol:         _Z9hymba_fwd4Args.kd
    .uniform_work_group_size: 1
    .uses_dynamic_stack: false
    .vgpr_count:     256
    .vgpr_spill_count: 0
    .wavefront_size: 64
